# MLA loops: rare rescale blocks moved out of line (common path has no taken branches)
# baseline (speedup 1.0000x reference)
.LBB0_710:
	s_mov_b32 s35, s4
	s_mov_b32 s4, s52
	global_load_dwordx4 v[204:207], v192, s[98:99] offset:128
	global_load_dwordx4 v[208:211], v188, s[98:99]
	global_load_dwordx2 v[218:219], v214, s[98:99] offset:-2048
	ds_read_b128 v[118:121], v199 offset:17424
	ds_read_b128 v[114:117], v199 offset:17408
	ds_read_b128 v[130:133], v199 offset:22016
	ds_read_b128 v[134:137], v199 offset:22032
	ds_read_b128 v[156:159], v199 offset:17488
	ds_read_b128 v[238:241], v199 offset:17472
	s_waitcnt lgkmcnt(4)
	v_add_f32_e32 v160, v86, v82
	v_mfma_scale_f32_32x32x64_f8f6f4 v[114:129], v[114:119], v[168:173], v[50:65], v120, v194 op_sel_hi:[0,0,0] cbsz:2 blgp:2
	v_cvt_pk_fp8_f32 v154, v82, v83
	v_cvt_pk_fp8_f32 v155, v98, v99
	v_cvt_pk_fp8_f32 v154, v84, v85 op_sel:[0,0,1]
	v_cvt_pk_fp8_f32 v155, v100, v101 op_sel:[0,0,1]
	v_add_f32_e32 v82, v87, v83
	v_add_f32_e32 v83, v88, v84
	v_permlane32_swap_b32_e32 v154, v155
	ds_read_b128 v[244:247], v199 offset:22080
	ds_read_b128 v[248:251], v199 offset:22096
	v_add_f32_e32 v84, v89, v85
	s_waitcnt lgkmcnt(3)
	v_mfma_scale_f32_32x32x64_f8f6f4 v[130:145], v[130:135], v[168:173], v[50:65], v136, v194 op_sel_hi:[0,0,0] cbsz:2 blgp:2
	v_add_f32_e32 v85, v90, v160
	v_add_f32_e32 v82, v91, v82
	v_mov_b32_e32 v242, v156
	v_mov_b32_e32 v243, v157
	v_add_f32_e32 v83, v92, v83
	v_add_f32_e32 v84, v93, v84
	v_add_f32_e32 v159, v94, v85
	v_add_f32_e32 v160, v95, v82
	v_add_f32_e32 v161, v96, v83
	v_add_f32_e32 v186, v97, v84
	ds_read_b128 v[230:233], v222 offset:5120
	ds_read_b128 v[234:237], v222 offset:5136
	s_waitcnt lgkmcnt(4)
	v_mfma_scale_f32_32x32x64_f8f6f4 v[114:129], v[238:243], v[162:167], v[114:129], v158, v190 op_sel_hi:[0,0,0] cbsz:2 blgp:2
	v_cvt_pk_fp8_f32 v156, v86, v87
	v_cvt_pk_fp8_f32 v157, v102, v103
	v_cvt_pk_fp8_f32 v156, v88, v89 op_sel:[0,0,1]
	v_cvt_pk_fp8_f32 v157, v104, v105 op_sel:[0,0,1]
	v_add_f32_e32 v98, v98, v159
	v_add_f32_e32 v99, v99, v160
	v_permlane32_swap_b32_e32 v156, v157
	v_add_f32_e32 v100, v100, v161
	v_add_f32_e32 v101, v101, v186
	v_add_f32_e32 v98, v102, v98
	ds_read_b128 v[82:85], v222 offset:7680
	ds_read_b128 v[86:89], v222 offset:7696
	s_waitcnt lgkmcnt(4)
	v_mfma_scale_f32_32x32x64_f8f6f4 v[130:145], v[244:249], v[162:167], v[130:145], v250, v190 op_sel_hi:[0,0,0] cbsz:2 blgp:2
	v_cvt_pk_fp8_f32 v158, v90, v91
	v_cvt_pk_fp8_f32 v159, v106, v107
	v_cvt_pk_fp8_f32 v158, v92, v93 op_sel:[0,0,1]
	v_cvt_pk_fp8_f32 v159, v108, v109 op_sel:[0,0,1]
	v_add_f32_e32 v90, v103, v99
	v_add_f32_e32 v91, v104, v100
	v_permlane32_swap_b32_e32 v158, v159
	v_add_f32_e32 v92, v105, v101
	s_waitcnt lgkmcnt(2)
	v_mfma_scale_f32_32x32x64_f8f6f4 v[114:129], v[230:237], v[146:153], v[114:129], v220, v1 op_sel_hi:[0,0,0]
	v_add_f32_e32 v93, v106, v98
	v_add_f32_e32 v90, v107, v90
	v_add_f32_e32 v91, v108, v91
	v_add_f32_e32 v92, v109, v92
	v_add_f32_e32 v93, v110, v93
	v_add_f32_e32 v90, v111, v90
	v_add_f32_e32 v91, v112, v91
	v_add_f32_e32 v92, v113, v92
	v_cvt_pk_fp8_f32 v160, v94, v95
	v_cvt_pk_fp8_f32 v161, v110, v111
	v_cvt_pk_fp8_f32 v160, v96, v97 op_sel:[0,0,1]
	v_cvt_pk_fp8_f32 v161, v112, v113 op_sel:[0,0,1]
	s_waitcnt lgkmcnt(0)
	v_mfma_scale_f32_32x32x64_f8f6f4 v[130:145], v[82:89], v[146:153], v[130:145], v220, v1 op_sel_hi:[0,0,0]
	v_add_f32_e32 v82, v93, v90
	v_add_f32_e32 v83, v91, v92
	v_permlane32_swap_b32_e32 v160, v161
	v_add_f32_e32 v229, v82, v83
	v_mov_b32_e32 v230, v229
	v_add_u32_e32 v82, s5, v224
	s_waitcnt vmcnt(0)
	ds_write_b128 v82, v[204:207]
	ds_write_b128 v225, v[208:211] offset:49152
	ds_write_b64 v226, v[218:219]
	v_add_u32_e32 v98, s4, v191
	ds_read_b128 v[90:93], v98
	ds_read_b128 v[94:97], v98 offset:16
	v_max3_f32 v82, v114, s88, v115
	v_max3_f32 v82, v82, v116, v117
	v_max3_f32 v82, v82, v118, v119
	v_permlane32_swap_b32_e32 v229, v230
	v_max3_f32 v99, v82, v120, v121
	ds_read_b128 v[82:85], v98 offset:2560
	ds_read_b128 v[86:89], v98 offset:2576
	v_max3_f32 v99, v99, v122, v123
	v_max3_f32 v99, v99, v124, v125
	v_max3_f32 v99, v99, v126, v127
	v_max3_f32 v99, v99, v128, v129
	s_waitcnt lgkmcnt(2)
	v_mfma_scale_f32_32x32x64_f8f6f4 v[66:81], v[90:97], v[154:161], v[66:81], v220, v220 op_sel_hi:[0,0,0]
	v_max3_f32 v99, v99, v130, v131
	v_max3_f32 v99, v99, v132, v133
	v_max3_f32 v99, v99, v134, v135
	v_max3_f32 v99, v99, v136, v137
	v_max3_f32 v99, v99, v138, v139
	v_max3_f32 v99, v99, v140, v141
	v_max3_f32 v99, v99, v142, v143
	v_max3_f32 v99, v99, v144, v145
	v_mov_b32_e32 v100, v99
	v_mov_b32_e32 v186, 1.0
	s_nop 0
	v_permlane32_swap_b32_e32 v99, v100
	v_max_f32_e32 v99, v99, v100
	v_cmp_ge_f32_e32 vcc, s89, v99
	s_cmp_eq_u64 vcc, exec
	s_cbranch_scc0 .Lmla0_slow0
.LBB0_712:
	s_waitcnt lgkmcnt(0)
	v_mfma_scale_f32_32x32x64_f8f6f4 v[34:49], v[82:89], v[154:161], v[34:49], v220, v220 op_sel_hi:[0,0,0]
	ds_read_b128 v[82:85], v98 offset:5120
	ds_read_b128 v[86:89], v98 offset:5136
	v_exp_f32_e32 v114, v114
	v_exp_f32_e32 v115, v115
	v_exp_f32_e32 v116, v116
	v_exp_f32_e32 v117, v117
	v_exp_f32_e32 v118, v118
	v_exp_f32_e32 v119, v119
	v_exp_f32_e32 v120, v120
	v_exp_f32_e32 v121, v121
	v_exp_f32_e32 v122, v122
	v_exp_f32_e32 v123, v123
	v_exp_f32_e32 v124, v124
	v_exp_f32_e32 v125, v125
	v_exp_f32_e32 v126, v126
	v_exp_f32_e32 v127, v127
	v_exp_f32_e32 v128, v128
	v_exp_f32_e32 v129, v129
	s_waitcnt lgkmcnt(0)
	v_mfma_scale_f32_32x32x64_f8f6f4 v[18:33], v[82:89], v[154:161], v[18:33], v220, v220 op_sel_hi:[0,0,0]
	ds_read_b128 v[82:85], v98 offset:7680
	ds_read_b128 v[86:89], v98 offset:7696
	v_exp_f32_e32 v130, v130
	v_exp_f32_e32 v131, v131
	v_exp_f32_e32 v132, v132
	v_exp_f32_e32 v133, v133
	v_exp_f32_e32 v134, v134
	v_exp_f32_e32 v135, v135
	v_exp_f32_e32 v136, v136
	v_exp_f32_e32 v137, v137
	v_exp_f32_e32 v138, v138
	v_exp_f32_e32 v139, v139
	v_exp_f32_e32 v140, v140
	v_exp_f32_e32 v141, v141
	v_exp_f32_e32 v142, v142
	v_exp_f32_e32 v143, v143
	v_exp_f32_e32 v144, v144
	v_exp_f32_e32 v145, v145
	s_waitcnt lgkmcnt(0)
	v_mfma_scale_f32_32x32x64_f8f6f4 v[2:17], v[82:89], v[154:161], v[2:17], v220, v220 op_sel_hi:[0,0,0]
	v_cmp_gt_f32_e32 vcc, 1.0, v186
	s_cbranch_vccnz .Lmla0_slow1
.LBB0_714:
	s_barrier
	global_load_dwordx4 v[204:207], v192, s[98:99] offset:192
	global_load_dwordx4 v[208:211], v189, s[98:99]
	global_load_dwordx2 v[196:197], v214, s[98:99] offset:2048
	ds_read_b128 v[86:89], v223 offset:49168
	ds_read_b128 v[82:85], v223 offset:49152
	ds_read_b128 v[98:101], v223 offset:53760
	ds_read_b128 v[102:105], v223 offset:53776
	ds_read_b128 v[156:159], v223 offset:49232
	ds_read_b128 v[240:243], v223 offset:49216
	s_waitcnt lgkmcnt(4)
	v_add_f32_e32 v160, v118, v114
	v_mfma_scale_f32_32x32x64_f8f6f4 v[82:97], v[82:87], v[174:179], v[50:65], v88, v198 op_sel_hi:[0,0,0] cbsz:2 blgp:2
	v_cvt_pk_fp8_f32 v154, v114, v115
	v_cvt_pk_fp8_f32 v155, v130, v131
	v_cvt_pk_fp8_f32 v154, v116, v117 op_sel:[0,0,1]
	v_cvt_pk_fp8_f32 v155, v132, v133 op_sel:[0,0,1]
	v_add_f32_e32 v114, v119, v115
	v_add_f32_e32 v115, v120, v116
	v_permlane32_swap_b32_e32 v154, v155
	ds_read_b128 v[246:249], v223 offset:53824
	ds_read_b128 v[216:219], v223 offset:53840
	v_add_f32_e32 v116, v121, v117
	s_waitcnt lgkmcnt(3)
	v_mfma_scale_f32_32x32x64_f8f6f4 v[98:113], v[98:103], v[174:179], v[50:65], v104, v198 op_sel_hi:[0,0,0] cbsz:2 blgp:2
	v_add_f32_e32 v117, v122, v160
	v_add_f32_e32 v114, v123, v114
	v_mov_b32_e32 v244, v156
	v_mov_b32_e32 v245, v157
	v_add_f32_e32 v115, v124, v115
	v_add_f32_e32 v116, v125, v116
	v_add_f32_e32 v159, v126, v117
	v_add_f32_e32 v160, v127, v114
	v_add_f32_e32 v161, v128, v115
	v_add_f32_e32 v200, v129, v116
	ds_read_b128 v[232:235], v222
	ds_read_b128 v[236:239], v222 offset:16
	s_waitcnt lgkmcnt(4)
	v_mfma_scale_f32_32x32x64_f8f6f4 v[82:97], v[240:245], v[180:185], v[82:97], v158, v202 op_sel_hi:[0,0,0] cbsz:2 blgp:2
	v_cvt_pk_fp8_f32 v156, v118, v119
	v_cvt_pk_fp8_f32 v157, v134, v135
	v_cvt_pk_fp8_f32 v156, v120, v121 op_sel:[0,0,1]
	v_cvt_pk_fp8_f32 v157, v136, v137 op_sel:[0,0,1]
	v_add_f32_e32 v130, v130, v159
	v_add_f32_e32 v131, v131, v160
	v_permlane32_swap_b32_e32 v156, v157
	s_waitcnt lgkmcnt(2)
	v_mov_b32_e32 v250, v216
	v_mov_b32_e32 v251, v217
	v_add_f32_e32 v132, v132, v161
	v_add_f32_e32 v133, v133, v200
	v_add_f32_e32 v130, v134, v130
	ds_read_b128 v[114:117], v222 offset:2560
	ds_read_b128 v[118:121], v222 offset:2576
	v_mfma_scale_f32_32x32x64_f8f6f4 v[98:113], v[246:251], v[180:185], v[98:113], v218, v202 op_sel_hi:[0,0,0] cbsz:2 blgp:2
	v_cvt_pk_fp8_f32 v158, v122, v123
	v_cvt_pk_fp8_f32 v159, v138, v139
	v_cvt_pk_fp8_f32 v158, v124, v125 op_sel:[0,0,1]
	v_cvt_pk_fp8_f32 v159, v140, v141 op_sel:[0,0,1]
	v_add_f32_e32 v122, v135, v131
	v_add_f32_e32 v123, v136, v132
	v_permlane32_swap_b32_e32 v158, v159
	v_add_f32_e32 v124, v137, v133
	s_waitcnt lgkmcnt(2)
	v_mfma_scale_f32_32x32x64_f8f6f4 v[82:97], v[232:239], v[146:153], v[82:97], v220, v1 op_sel_hi:[0,0,0]
	v_add_f32_e32 v125, v138, v130
	v_add_f32_e32 v122, v139, v122
	v_add_f32_e32 v123, v140, v123
	v_add_f32_e32 v124, v141, v124
	v_add_f32_e32 v125, v142, v125
	v_add_f32_e32 v122, v143, v122
	v_add_f32_e32 v123, v144, v123
	v_add_f32_e32 v124, v145, v124
	v_cvt_pk_fp8_f32 v160, v126, v127
	v_cvt_pk_fp8_f32 v161, v142, v143
	v_cvt_pk_fp8_f32 v160, v128, v129 op_sel:[0,0,1]
	v_cvt_pk_fp8_f32 v161, v144, v145 op_sel:[0,0,1]
	s_waitcnt lgkmcnt(0)
	v_mfma_scale_f32_32x32x64_f8f6f4 v[98:113], v[114:121], v[146:153], v[98:113], v220, v1 op_sel_hi:[0,0,0]
	v_add_f32_e32 v114, v125, v122
	v_add_f32_e32 v115, v123, v124
	v_permlane32_swap_b32_e32 v160, v161
	v_add_f32_e32 v130, v114, v115
	v_mov_b32_e32 v131, v130
	v_add_u32_e32 v114, s4, v224
	s_waitcnt vmcnt(0)
	ds_write_b128 v114, v[204:207]
	ds_write_b128 v203, v[208:211]
	ds_write_b64 v227, v[196:197]
	v_add_u32_e32 v132, s35, v191
	ds_read_b128 v[122:125], v132
	ds_read_b128 v[126:129], v132 offset:16
	v_max3_f32 v114, v82, s88, v83
	v_max3_f32 v114, v114, v84, v85
	v_max3_f32 v114, v114, v86, v87
	v_permlane32_swap_b32_e32 v130, v131
	v_max3_f32 v133, v114, v88, v89
	ds_read_b128 v[114:117], v132 offset:2560
	ds_read_b128 v[118:121], v132 offset:2576
	v_max3_f32 v133, v133, v90, v91
	v_max3_f32 v133, v133, v92, v93
	v_max3_f32 v133, v133, v94, v95
	v_max3_f32 v133, v133, v96, v97
	s_waitcnt lgkmcnt(2)
	v_mfma_scale_f32_32x32x64_f8f6f4 v[66:81], v[122:129], v[154:161], v[66:81], v220, v220 op_sel_hi:[0,0,0]
	v_max3_f32 v133, v133, v98, v99
	v_max3_f32 v133, v133, v100, v101
	v_max3_f32 v133, v133, v102, v103
	v_max3_f32 v133, v133, v104, v105
	v_max3_f32 v133, v133, v106, v107
	v_max3_f32 v133, v133, v108, v109
	v_max3_f32 v133, v133, v110, v111
	v_max3_f32 v133, v133, v112, v113
	v_mov_b32_e32 v134, v133
	v_mov_b32_e32 v138, 1.0
	s_nop 0
	v_permlane32_swap_b32_e32 v133, v134
	v_max_f32_e32 v133, v133, v134
	v_cmp_ge_f32_e32 vcc, s89, v133
	s_cmp_eq_u64 vcc, exec
	s_cbranch_scc0 .Lmla0_slow2
.LBB0_716:
	s_waitcnt lgkmcnt(0)
	v_mfma_scale_f32_32x32x64_f8f6f4 v[34:49], v[114:121], v[154:161], v[34:49], v220, v220 op_sel_hi:[0,0,0]
	ds_read_b128 v[114:117], v132 offset:5120
	ds_read_b128 v[118:121], v132 offset:5136
	v_exp_f32_e32 v82, v82
	v_exp_f32_e32 v83, v83
	v_exp_f32_e32 v84, v84
	v_exp_f32_e32 v85, v85
	v_exp_f32_e32 v86, v86
	v_exp_f32_e32 v87, v87
	v_exp_f32_e32 v88, v88
	v_exp_f32_e32 v89, v89
	v_exp_f32_e32 v90, v90
	v_exp_f32_e32 v91, v91
	v_exp_f32_e32 v92, v92
	v_exp_f32_e32 v93, v93
	v_exp_f32_e32 v94, v94
	v_exp_f32_e32 v95, v95
	v_exp_f32_e32 v96, v96
	v_exp_f32_e32 v97, v97
	s_waitcnt lgkmcnt(0)
	v_mfma_scale_f32_32x32x64_f8f6f4 v[18:33], v[114:121], v[154:161], v[18:33], v220, v220 op_sel_hi:[0,0,0]
	ds_read_b128 v[114:117], v132 offset:7680
	ds_read_b128 v[118:121], v132 offset:7696
	v_exp_f32_e32 v98, v98
	v_exp_f32_e32 v99, v99
	v_exp_f32_e32 v100, v100
	v_exp_f32_e32 v101, v101
	v_exp_f32_e32 v102, v102
	v_exp_f32_e32 v103, v103
	v_exp_f32_e32 v104, v104
	v_exp_f32_e32 v105, v105
	v_exp_f32_e32 v106, v106
	v_exp_f32_e32 v107, v107
	v_exp_f32_e32 v108, v108
	v_exp_f32_e32 v109, v109
	v_exp_f32_e32 v110, v110
	v_exp_f32_e32 v111, v111
	v_exp_f32_e32 v112, v112
	v_exp_f32_e32 v113, v113
	s_waitcnt lgkmcnt(0)
	v_mfma_scale_f32_32x32x64_f8f6f4 v[2:17], v[114:121], v[154:161], v[2:17], v220, v220 op_sel_hi:[0,0,0]
	v_cmp_gt_f32_e32 vcc, 1.0, v138
	s_cbranch_vccnz .Lmla0_slow3

.Lmla0_slow0:
	v_add_f32_e32 v99, -4.0, v99
	v_max_f32_e32 v99, 0, v99
	v_exp_f32_e64 v186, -v99
	v_sub_f32_e32 v129, v129, v99
	v_sub_f32_e32 v128, v128, v99
	v_sub_f32_e32 v127, v127, v99
	v_sub_f32_e32 v126, v126, v99
	v_sub_f32_e32 v125, v125, v99
	v_sub_f32_e32 v124, v124, v99
	v_sub_f32_e32 v123, v123, v99
	v_sub_f32_e32 v122, v122, v99
	v_sub_f32_e32 v121, v121, v99
	v_sub_f32_e32 v120, v120, v99
	v_sub_f32_e32 v119, v119, v99
	v_sub_f32_e32 v118, v118, v99
	v_sub_f32_e32 v117, v117, v99
	v_sub_f32_e32 v116, v116, v99
	v_sub_f32_e32 v115, v115, v99
	v_sub_f32_e32 v114, v114, v99
	v_sub_f32_e32 v145, v145, v99
	v_sub_f32_e32 v144, v144, v99
	v_sub_f32_e32 v143, v143, v99
	v_sub_f32_e32 v142, v142, v99
	v_sub_f32_e32 v141, v141, v99
	v_sub_f32_e32 v140, v140, v99
	v_sub_f32_e32 v139, v139, v99
	v_sub_f32_e32 v138, v138, v99
	v_sub_f32_e32 v137, v137, v99
	v_sub_f32_e32 v136, v136, v99
	v_sub_f32_e32 v135, v135, v99
	v_sub_f32_e32 v134, v134, v99
	v_sub_f32_e32 v133, v133, v99
	v_sub_f32_e32 v132, v132, v99
	v_sub_f32_e32 v131, v131, v99
	v_sub_f32_e32 v130, v130, v99
	v_sub_f32_e32 v65, v65, v99
	v_sub_f32_e32 v64, v64, v99
	v_sub_f32_e32 v63, v63, v99
	v_sub_f32_e32 v62, v62, v99
	v_sub_f32_e32 v61, v61, v99
	v_sub_f32_e32 v60, v60, v99
	v_sub_f32_e32 v59, v59, v99
	v_sub_f32_e32 v58, v58, v99
	v_sub_f32_e32 v57, v57, v99
	v_sub_f32_e32 v56, v56, v99
	v_sub_f32_e32 v55, v55, v99
	v_sub_f32_e32 v54, v54, v99
	v_sub_f32_e32 v53, v53, v99
	v_sub_f32_e32 v52, v52, v99
	v_sub_f32_e32 v51, v51, v99
	v_sub_f32_e32 v50, v50, v99
	s_branch .LBB0_712
.Lmla0_slow1:
	v_pk_mul_f32 v[80:81], v[80:81], v[186:187] op_sel_hi:[1,0]
	v_pk_mul_f32 v[78:79], v[78:79], v[186:187] op_sel_hi:[1,0]
	v_pk_mul_f32 v[76:77], v[76:77], v[186:187] op_sel_hi:[1,0]
	v_pk_mul_f32 v[74:75], v[74:75], v[186:187] op_sel_hi:[1,0]
	v_pk_mul_f32 v[72:73], v[72:73], v[186:187] op_sel_hi:[1,0]
	v_pk_mul_f32 v[70:71], v[70:71], v[186:187] op_sel_hi:[1,0]
	v_pk_mul_f32 v[68:69], v[68:69], v[186:187] op_sel_hi:[1,0]
	v_pk_mul_f32 v[66:67], v[66:67], v[186:187] op_sel_hi:[1,0]
	v_pk_mul_f32 v[48:49], v[48:49], v[186:187] op_sel_hi:[1,0]
	v_pk_mul_f32 v[46:47], v[46:47], v[186:187] op_sel_hi:[1,0]
	v_pk_mul_f32 v[44:45], v[44:45], v[186:187] op_sel_hi:[1,0]
	v_pk_mul_f32 v[42:43], v[42:43], v[186:187] op_sel_hi:[1,0]
	v_pk_mul_f32 v[40:41], v[40:41], v[186:187] op_sel_hi:[1,0]
	v_pk_mul_f32 v[38:39], v[38:39], v[186:187] op_sel_hi:[1,0]
	v_pk_mul_f32 v[36:37], v[36:37], v[186:187] op_sel_hi:[1,0]
	v_pk_mul_f32 v[34:35], v[34:35], v[186:187] op_sel_hi:[1,0]
	v_pk_mul_f32 v[32:33], v[186:187], v[32:33] op_sel_hi:[0,1]
	v_pk_mul_f32 v[30:31], v[186:187], v[30:31] op_sel_hi:[0,1]
	v_pk_mul_f32 v[28:29], v[186:187], v[28:29] op_sel_hi:[0,1]
	v_pk_mul_f32 v[26:27], v[186:187], v[26:27] op_sel_hi:[0,1]
	v_pk_mul_f32 v[24:25], v[186:187], v[24:25] op_sel_hi:[0,1]
	v_pk_mul_f32 v[22:23], v[186:187], v[22:23] op_sel_hi:[0,1]
	v_pk_mul_f32 v[20:21], v[186:187], v[20:21] op_sel_hi:[0,1]
	v_pk_mul_f32 v[18:19], v[186:187], v[18:19] op_sel_hi:[0,1]
	v_pk_mul_f32 v[16:17], v[186:187], v[16:17] op_sel_hi:[0,1]
	v_pk_mul_f32 v[14:15], v[186:187], v[14:15] op_sel_hi:[0,1]
	v_pk_mul_f32 v[12:13], v[186:187], v[12:13] op_sel_hi:[0,1]
	v_pk_mul_f32 v[10:11], v[186:187], v[10:11] op_sel_hi:[0,1]
	v_pk_mul_f32 v[8:9], v[186:187], v[8:9] op_sel_hi:[0,1]
	v_pk_mul_f32 v[6:7], v[186:187], v[6:7] op_sel_hi:[0,1]
	v_pk_mul_f32 v[4:5], v[186:187], v[4:5] op_sel_hi:[0,1]
	v_pk_mul_f32 v[2:3], v[186:187], v[2:3] op_sel_hi:[0,1]
	s_branch .LBB0_714
.Lmla0_slow2:
	v_add_f32_e32 v133, -4.0, v133
	v_max_f32_e32 v133, 0, v133
	v_exp_f32_e64 v138, -v133
	v_sub_f32_e32 v97, v97, v133
	v_sub_f32_e32 v96, v96, v133
	v_sub_f32_e32 v95, v95, v133
	v_sub_f32_e32 v94, v94, v133
	v_sub_f32_e32 v93, v93, v133
	v_sub_f32_e32 v92, v92, v133
	v_sub_f32_e32 v91, v91, v133
	v_sub_f32_e32 v90, v90, v133
	v_sub_f32_e32 v89, v89, v133
	v_sub_f32_e32 v88, v88, v133
	v_sub_f32_e32 v87, v87, v133
	v_sub_f32_e32 v86, v86, v133
	v_sub_f32_e32 v85, v85, v133
	v_sub_f32_e32 v84, v84, v133
	v_sub_f32_e32 v83, v83, v133
	v_sub_f32_e32 v82, v82, v133
	v_sub_f32_e32 v113, v113, v133
	v_sub_f32_e32 v112, v112, v133
	v_sub_f32_e32 v111, v111, v133
	v_sub_f32_e32 v110, v110, v133
	v_sub_f32_e32 v109, v109, v133
	v_sub_f32_e32 v108, v108, v133
	v_sub_f32_e32 v107, v107, v133
	v_sub_f32_e32 v106, v106, v133
	v_sub_f32_e32 v105, v105, v133
	v_sub_f32_e32 v104, v104, v133
	v_sub_f32_e32 v103, v103, v133
	v_sub_f32_e32 v102, v102, v133
	v_sub_f32_e32 v101, v101, v133
	v_sub_f32_e32 v100, v100, v133
	v_sub_f32_e32 v99, v99, v133
	v_sub_f32_e32 v98, v98, v133
	v_sub_f32_e32 v65, v65, v133
	v_sub_f32_e32 v64, v64, v133
	v_sub_f32_e32 v63, v63, v133
	v_sub_f32_e32 v62, v62, v133
	v_sub_f32_e32 v61, v61, v133
	v_sub_f32_e32 v60, v60, v133
	v_sub_f32_e32 v59, v59, v133
	v_sub_f32_e32 v58, v58, v133
	v_sub_f32_e32 v57, v57, v133
	v_sub_f32_e32 v56, v56, v133
	v_sub_f32_e32 v55, v55, v133
	v_sub_f32_e32 v54, v54, v133
	v_sub_f32_e32 v53, v53, v133
	v_sub_f32_e32 v52, v52, v133
	v_sub_f32_e32 v51, v51, v133
	v_sub_f32_e32 v50, v50, v133
	s_branch .LBB0_716
.Lmla0_slow3:
	v_pk_mul_f32 v[80:81], v[80:81], v[138:139] op_sel_hi:[1,0]
	v_pk_mul_f32 v[78:79], v[78:79], v[138:139] op_sel_hi:[1,0]
	v_pk_mul_f32 v[76:77], v[76:77], v[138:139] op_sel_hi:[1,0]
	v_pk_mul_f32 v[74:75], v[74:75], v[138:139] op_sel_hi:[1,0]
	v_pk_mul_f32 v[72:73], v[72:73], v[138:139] op_sel_hi:[1,0]
	v_pk_mul_f32 v[70:71], v[70:71], v[138:139] op_sel_hi:[1,0]
	v_pk_mul_f32 v[68:69], v[68:69], v[138:139] op_sel_hi:[1,0]
	v_pk_mul_f32 v[66:67], v[66:67], v[138:139] op_sel_hi:[1,0]
	v_pk_mul_f32 v[48:49], v[48:49], v[138:139] op_sel_hi:[1,0]
	v_pk_mul_f32 v[46:47], v[46:47], v[138:139] op_sel_hi:[1,0]
	v_pk_mul_f32 v[44:45], v[44:45], v[138:139] op_sel_hi:[1,0]
	v_pk_mul_f32 v[42:43], v[42:43], v[138:139] op_sel_hi:[1,0]
	v_pk_mul_f32 v[40:41], v[40:41], v[138:139] op_sel_hi:[1,0]
	v_pk_mul_f32 v[38:39], v[38:39], v[138:139] op_sel_hi:[1,0]
	v_pk_mul_f32 v[36:37], v[36:37], v[138:139] op_sel_hi:[1,0]
	v_pk_mul_f32 v[34:35], v[34:35], v[138:139] op_sel_hi:[1,0]
	v_pk_mul_f32 v[32:33], v[138:139], v[32:33] op_sel_hi:[0,1]
	v_pk_mul_f32 v[30:31], v[138:139], v[30:31] op_sel_hi:[0,1]
	v_pk_mul_f32 v[28:29], v[138:139], v[28:29] op_sel_hi:[0,1]
	v_pk_mul_f32 v[26:27], v[138:139], v[26:27] op_sel_hi:[0,1]
	v_pk_mul_f32 v[24:25], v[138:139], v[24:25] op_sel_hi:[0,1]
	v_pk_mul_f32 v[22:23], v[138:139], v[22:23] op_sel_hi:[0,1]
	v_pk_mul_f32 v[20:21], v[138:139], v[20:21] op_sel_hi:[0,1]
	v_pk_mul_f32 v[18:19], v[138:139], v[18:19] op_sel_hi:[0,1]
	v_pk_mul_f32 v[16:17], v[138:139], v[16:17] op_sel_hi:[0,1]
	v_pk_mul_f32 v[14:15], v[138:139], v[14:15] op_sel_hi:[0,1]
	v_pk_mul_f32 v[12:13], v[138:139], v[12:13] op_sel_hi:[0,1]
	v_pk_mul_f32 v[10:11], v[138:139], v[10:11] op_sel_hi:[0,1]
	v_pk_mul_f32 v[8:9], v[138:139], v[8:9] op_sel_hi:[0,1]
	v_pk_mul_f32 v[6:7], v[138:139], v[6:7] op_sel_hi:[0,1]
	v_pk_mul_f32 v[4:5], v[138:139], v[4:5] op_sel_hi:[0,1]
	v_pk_mul_f32 v[2:3], v[138:139], v[2:3] op_sel_hi:[0,1]
	s_branch .LBB0_718

.LBB0_1733:
	s_mov_b32 s10, s4
	s_mov_b32 s4, s8
	global_load_dwordx4 v[204:207], v192, s[98:99] offset:128
	global_load_dwordx4 v[208:211], v188, s[98:99]
	global_load_dwordx2 v[218:219], v214, s[98:99] offset:-2048
	ds_read_b128 v[118:121], v199 offset:17424
	ds_read_b128 v[114:117], v199 offset:17408
	ds_read_b128 v[130:133], v199 offset:22016
	ds_read_b128 v[134:137], v199 offset:22032
	ds_read_b128 v[156:159], v199 offset:17488
	ds_read_b128 v[238:241], v199 offset:17472
	s_waitcnt lgkmcnt(4)
	v_add_f32_e32 v160, v86, v82
	v_mfma_scale_f32_32x32x64_f8f6f4 v[114:129], v[114:119], v[168:173], v[50:65], v120, v194 op_sel_hi:[0,0,0] cbsz:2 blgp:2
	v_cvt_pk_fp8_f32 v154, v82, v83
	v_cvt_pk_fp8_f32 v155, v98, v99
	v_cvt_pk_fp8_f32 v154, v84, v85 op_sel:[0,0,1]
	v_cvt_pk_fp8_f32 v155, v100, v101 op_sel:[0,0,1]
	v_add_f32_e32 v82, v87, v83
	v_add_f32_e32 v83, v88, v84
	v_permlane32_swap_b32_e32 v154, v155
	ds_read_b128 v[244:247], v199 offset:22080
	ds_read_b128 v[248:251], v199 offset:22096
	v_add_f32_e32 v84, v89, v85
	s_waitcnt lgkmcnt(3)
	v_mfma_scale_f32_32x32x64_f8f6f4 v[130:145], v[130:135], v[168:173], v[50:65], v136, v194 op_sel_hi:[0,0,0] cbsz:2 blgp:2
	v_add_f32_e32 v85, v90, v160
	v_add_f32_e32 v82, v91, v82
	v_mov_b32_e32 v242, v156
	v_mov_b32_e32 v243, v157
	v_add_f32_e32 v83, v92, v83
	v_add_f32_e32 v84, v93, v84
	v_add_f32_e32 v159, v94, v85
	v_add_f32_e32 v160, v95, v82
	v_add_f32_e32 v161, v96, v83
	v_add_f32_e32 v186, v97, v84
	ds_read_b128 v[230:233], v222 offset:5120
	ds_read_b128 v[234:237], v222 offset:5136
	s_waitcnt lgkmcnt(4)
	v_mfma_scale_f32_32x32x64_f8f6f4 v[114:129], v[238:243], v[162:167], v[114:129], v158, v190 op_sel_hi:[0,0,0] cbsz:2 blgp:2
	v_cvt_pk_fp8_f32 v156, v86, v87
	v_cvt_pk_fp8_f32 v157, v102, v103
	v_cvt_pk_fp8_f32 v156, v88, v89 op_sel:[0,0,1]
	v_cvt_pk_fp8_f32 v157, v104, v105 op_sel:[0,0,1]
	v_add_f32_e32 v98, v98, v159
	v_add_f32_e32 v99, v99, v160
	v_permlane32_swap_b32_e32 v156, v157
	v_add_f32_e32 v100, v100, v161
	v_add_f32_e32 v101, v101, v186
	v_add_f32_e32 v98, v102, v98
	ds_read_b128 v[82:85], v222 offset:7680
	ds_read_b128 v[86:89], v222 offset:7696
	s_waitcnt lgkmcnt(4)
	v_mfma_scale_f32_32x32x64_f8f6f4 v[130:145], v[244:249], v[162:167], v[130:145], v250, v190 op_sel_hi:[0,0,0] cbsz:2 blgp:2
	v_cvt_pk_fp8_f32 v158, v90, v91
	v_cvt_pk_fp8_f32 v159, v106, v107
	v_cvt_pk_fp8_f32 v158, v92, v93 op_sel:[0,0,1]
	v_cvt_pk_fp8_f32 v159, v108, v109 op_sel:[0,0,1]
	v_add_f32_e32 v90, v103, v99
	v_add_f32_e32 v91, v104, v100
	v_permlane32_swap_b32_e32 v158, v159
	v_add_f32_e32 v92, v105, v101
	s_waitcnt lgkmcnt(2)
	v_mfma_scale_f32_32x32x64_f8f6f4 v[114:129], v[230:237], v[146:153], v[114:129], v220, v1 op_sel_hi:[0,0,0]
	v_add_f32_e32 v93, v106, v98
	v_add_f32_e32 v90, v107, v90
	v_add_f32_e32 v91, v108, v91
	v_add_f32_e32 v92, v109, v92
	v_add_f32_e32 v93, v110, v93
	v_add_f32_e32 v90, v111, v90
	v_add_f32_e32 v91, v112, v91
	v_add_f32_e32 v92, v113, v92
	v_cvt_pk_fp8_f32 v160, v94, v95
	v_cvt_pk_fp8_f32 v161, v110, v111
	v_cvt_pk_fp8_f32 v160, v96, v97 op_sel:[0,0,1]
	v_cvt_pk_fp8_f32 v161, v112, v113 op_sel:[0,0,1]
	s_waitcnt lgkmcnt(0)
	v_mfma_scale_f32_32x32x64_f8f6f4 v[130:145], v[82:89], v[146:153], v[130:145], v220, v1 op_sel_hi:[0,0,0]
	v_add_f32_e32 v82, v93, v90
	v_add_f32_e32 v83, v91, v92
	v_permlane32_swap_b32_e32 v160, v161
	v_add_f32_e32 v229, v82, v83
	v_mov_b32_e32 v230, v229
	v_add_u32_e32 v82, s5, v224
	s_waitcnt vmcnt(0)
	ds_write_b128 v82, v[204:207]
	ds_write_b128 v225, v[208:211] offset:49152
	ds_write_b64 v226, v[218:219]
	v_add_u32_e32 v98, s4, v191
	ds_read_b128 v[90:93], v98
	ds_read_b128 v[94:97], v98 offset:16
	v_max3_f32 v82, v114, s87, v115
	v_max3_f32 v82, v82, v116, v117
	v_max3_f32 v82, v82, v118, v119
	v_permlane32_swap_b32_e32 v229, v230
	v_max3_f32 v99, v82, v120, v121
	ds_read_b128 v[82:85], v98 offset:2560
	ds_read_b128 v[86:89], v98 offset:2576
	v_max3_f32 v99, v99, v122, v123
	v_max3_f32 v99, v99, v124, v125
	v_max3_f32 v99, v99, v126, v127
	v_max3_f32 v99, v99, v128, v129
	s_waitcnt lgkmcnt(2)
	v_mfma_scale_f32_32x32x64_f8f6f4 v[66:81], v[90:97], v[154:161], v[66:81], v220, v220 op_sel_hi:[0,0,0]
	v_max3_f32 v99, v99, v130, v131
	v_max3_f32 v99, v99, v132, v133
	v_max3_f32 v99, v99, v134, v135
	v_max3_f32 v99, v99, v136, v137
	v_max3_f32 v99, v99, v138, v139
	v_max3_f32 v99, v99, v140, v141
	v_max3_f32 v99, v99, v142, v143
	v_max3_f32 v99, v99, v144, v145
	v_mov_b32_e32 v100, v99
	v_mov_b32_e32 v186, 1.0
	s_nop 0
	v_permlane32_swap_b32_e32 v99, v100
	v_max_f32_e32 v99, v99, v100
	v_cmp_ge_f32_e32 vcc, s88, v99
	s_cmp_eq_u64 vcc, exec
	s_cbranch_scc0 .Lmla1_slow0

.LBB0_1737:
	s_barrier
	global_load_dwordx4 v[204:207], v192, s[98:99] offset:192
	global_load_dwordx4 v[208:211], v189, s[98:99]
	global_load_dwordx2 v[196:197], v214, s[98:99] offset:2048
	ds_read_b128 v[86:89], v223 offset:49168
	ds_read_b128 v[82:85], v223 offset:49152
	ds_read_b128 v[98:101], v223 offset:53760
	ds_read_b128 v[102:105], v223 offset:53776
	ds_read_b128 v[156:159], v223 offset:49232
	ds_read_b128 v[240:243], v223 offset:49216
	s_waitcnt lgkmcnt(4)
	v_add_f32_e32 v160, v118, v114
	v_mfma_scale_f32_32x32x64_f8f6f4 v[82:97], v[82:87], v[174:179], v[50:65], v88, v198 op_sel_hi:[0,0,0] cbsz:2 blgp:2
	v_cvt_pk_fp8_f32 v154, v114, v115
	v_cvt_pk_fp8_f32 v155, v130, v131
	v_cvt_pk_fp8_f32 v154, v116, v117 op_sel:[0,0,1]
	v_cvt_pk_fp8_f32 v155, v132, v133 op_sel:[0,0,1]
	v_add_f32_e32 v114, v119, v115
	v_add_f32_e32 v115, v120, v116
	v_permlane32_swap_b32_e32 v154, v155
	ds_read_b128 v[246:249], v223 offset:53824
	ds_read_b128 v[216:219], v223 offset:53840
	v_add_f32_e32 v116, v121, v117
	s_waitcnt lgkmcnt(3)
	v_mfma_scale_f32_32x32x64_f8f6f4 v[98:113], v[98:103], v[174:179], v[50:65], v104, v198 op_sel_hi:[0,0,0] cbsz:2 blgp:2
	v_add_f32_e32 v117, v122, v160
	v_add_f32_e32 v114, v123, v114
	v_mov_b32_e32 v244, v156
	v_mov_b32_e32 v245, v157
	v_add_f32_e32 v115, v124, v115
	v_add_f32_e32 v116, v125, v116
	v_add_f32_e32 v159, v126, v117
	v_add_f32_e32 v160, v127, v114
	v_add_f32_e32 v161, v128, v115
	v_add_f32_e32 v200, v129, v116
	ds_read_b128 v[232:235], v222
	ds_read_b128 v[236:239], v222 offset:16
	s_waitcnt lgkmcnt(4)
	v_mfma_scale_f32_32x32x64_f8f6f4 v[82:97], v[240:245], v[180:185], v[82:97], v158, v202 op_sel_hi:[0,0,0] cbsz:2 blgp:2
	v_cvt_pk_fp8_f32 v156, v118, v119
	v_cvt_pk_fp8_f32 v157, v134, v135
	v_cvt_pk_fp8_f32 v156, v120, v121 op_sel:[0,0,1]
	v_cvt_pk_fp8_f32 v157, v136, v137 op_sel:[0,0,1]
	v_add_f32_e32 v130, v130, v159
	v_add_f32_e32 v131, v131, v160
	v_permlane32_swap_b32_e32 v156, v157
	s_waitcnt lgkmcnt(2)
	v_mov_b32_e32 v250, v216
	v_mov_b32_e32 v251, v217
	v_add_f32_e32 v132, v132, v161
	v_add_f32_e32 v133, v133, v200
	v_add_f32_e32 v130, v134, v130
	ds_read_b128 v[114:117], v222 offset:2560
	ds_read_b128 v[118:121], v222 offset:2576
	v_mfma_scale_f32_32x32x64_f8f6f4 v[98:113], v[246:251], v[180:185], v[98:113], v218, v202 op_sel_hi:[0,0,0] cbsz:2 blgp:2
	v_cvt_pk_fp8_f32 v158, v122, v123
	v_cvt_pk_fp8_f32 v159, v138, v139
	v_cvt_pk_fp8_f32 v158, v124, v125 op_sel:[0,0,1]
	v_cvt_pk_fp8_f32 v159, v140, v141 op_sel:[0,0,1]
	v_add_f32_e32 v122, v135, v131
	v_add_f32_e32 v123, v136, v132
	v_permlane32_swap_b32_e32 v158, v159
	v_add_f32_e32 v124, v137, v133
	s_waitcnt lgkmcnt(2)
	v_mfma_scale_f32_32x32x64_f8f6f4 v[82:97], v[232:239], v[146:153], v[82:97], v220, v1 op_sel_hi:[0,0,0]
	v_add_f32_e32 v125, v138, v130
	v_add_f32_e32 v122, v139, v122
	v_add_f32_e32 v123, v140, v123
	v_add_f32_e32 v124, v141, v124
	v_add_f32_e32 v125, v142, v125
	v_add_f32_e32 v122, v143, v122
	v_add_f32_e32 v123, v144, v123
	v_add_f32_e32 v124, v145, v124
	v_cvt_pk_fp8_f32 v160, v126, v127
	v_cvt_pk_fp8_f32 v161, v142, v143
	v_cvt_pk_fp8_f32 v160, v128, v129 op_sel:[0,0,1]
	v_cvt_pk_fp8_f32 v161, v144, v145 op_sel:[0,0,1]
	s_waitcnt lgkmcnt(0)
	v_mfma_scale_f32_32x32x64_f8f6f4 v[98:113], v[114:121], v[146:153], v[98:113], v220, v1 op_sel_hi:[0,0,0]
	v_add_f32_e32 v114, v125, v122
	v_add_f32_e32 v115, v123, v124
	v_permlane32_swap_b32_e32 v160, v161
	v_add_f32_e32 v130, v114, v115
	v_mov_b32_e32 v131, v130
	v_add_u32_e32 v114, s4, v224
	s_waitcnt vmcnt(0)
	ds_write_b128 v114, v[204:207]
	ds_write_b128 v203, v[208:211]
	ds_write_b64 v227, v[196:197]
	v_add_u32_e32 v132, s10, v191
	ds_read_b128 v[122:125], v132
	ds_read_b128 v[126:129], v132 offset:16
	v_max3_f32 v114, v82, s87, v83
	v_max3_f32 v114, v114, v84, v85
	v_max3_f32 v114, v114, v86, v87
	v_permlane32_swap_b32_e32 v130, v131
	v_max3_f32 v133, v114, v88, v89
	ds_read_b128 v[114:117], v132 offset:2560
	ds_read_b128 v[118:121], v132 offset:2576
	v_max3_f32 v133, v133, v90, v91
	v_max3_f32 v133, v133, v92, v93
	v_max3_f32 v133, v133, v94, v95
	v_max3_f32 v133, v133, v96, v97
	s_waitcnt lgkmcnt(2)
	v_mfma_scale_f32_32x32x64_f8f6f4 v[66:81], v[122:129], v[154:161], v[66:81], v220, v220 op_sel_hi:[0,0,0]
	v_max3_f32 v133, v133, v98, v99
	v_max3_f32 v133, v133, v100, v101
	v_max3_f32 v133, v133, v102, v103
	v_max3_f32 v133, v133, v104, v105
	v_max3_f32 v133, v133, v106, v107
	v_max3_f32 v133, v133, v108, v109
	v_max3_f32 v133, v133, v110, v111
	v_max3_f32 v133, v133, v112, v113
	v_mov_b32_e32 v134, v133
	v_mov_b32_e32 v138, 1.0
	s_nop 0
	v_permlane32_swap_b32_e32 v133, v134
	v_max_f32_e32 v133, v133, v134
	v_cmp_ge_f32_e32 vcc, s88, v133
	s_cmp_eq_u64 vcc, exec
	s_cbranch_scc0 .Lmla1_slow2
